# conversion routine: adjacent items spread across workgroups (a workgroup's waves take items NGW/8 apart)
# baseline (speedup 1.0000x reference)
;     ...
;         const int nitems = (K >> 6) * (N >> 5);
;         int ilo = 0, ihi = nitems; if ((fmask >> mi) & 1u) { ilo = (nitems * flo) >> 4; ihi = (nitems * fhi) >> 4; }
;         const int cnt = ihi - ilo;
;         int first = (gw - base) % NGW; if (first < 0) first += NGW;
;         for (int it = first; it < cnt; it += NGW) tr_item(W, K, N, WT, ks, rm, ilo + it, lane);
;         base = (base + cnt) % NGW;
; __global__ void __launch_bounds__(NTHREADS, 2) mk_fwd(Args args) {
;     ...
;     if (KON(0) && IN(0)) { const int vcu = (G % 8 == 0) ? (blk % 8) * (G / 8) + blk / 8 : blk; p0_prologue(args, vcu * NWAVES + wave, G * NWAVES, lane, 0x000Fu | 0x0010u | 0x0800u, true, 0x0810u, 0, 10); }
.LBB0_8:
	s_lshl_b32 s4, s4, 3
	s_add_i32 s12, s4, s2
	s_lshl_b32 s14, s3, 3
	s_add_u32 s15, s92, 0x5e00000
	s_addc_u32 s26, s93, 0
	s_add_u32 s27, s92, 0x4e00000
	s_addc_u32 s28, s93, 0
	s_add_u32 s29, s92, 0x4600000
	s_addc_u32 s30, s93, 0
	s_add_u32 s31, s92, 0x3e00000
	s_addc_u32 s33, s93, 0
	s_add_u32 s34, s92, 0x200000
	s_addc_u32 s35, s93, 0
	s_add_u32 s36, s92, 0xb600000
	s_addc_u32 s37, s93, 0
	s_abs_i32 s38, s14
	v_cvt_f32_u32_e32 v1, s38
	s_sub_i32 s4, 0, s38
	v_lshlrev_b32_e32 v3, 2, v204
	v_and_b32_e32 v38, 56, v204
	v_rcp_iflag_f32_e32 v2, v1
	v_and_b32_e32 v1, 7, v204
	v_and_b32_e32 v39, 28, v3
	s_lshl_b32 s9, s3, 9
	v_mul_f32_e32 v2, 0x4f7ffffe, v2
	v_cvt_u32_f32_e32 v2, v2
	s_lshl_b32 s39, s3, 8
	s_movk_i32 s41, 0xf00
	s_movk_i32 s42, 0xe00
	v_readfirstlane_b32 s5, v2
	s_mul_i32 s4, s4, s5
	s_mul_hi_u32 s4, s5, s4
	v_mov_b32_e32 v2, 0xffffe400
	s_add_i32 s40, s5, s4
	v_lshl_or_b32 v40, v1, 3, v2
	s_cmpk_lg_u32 s3, 0x100
	s_cbranch_scc1 .Lslot_p0_orig
	v_and_b32_e32 v43, 63, v204
	v_lshrrev_b32_e32 v102, 3, v43
	v_and_b32_e32 v103, 7, v43
	s_and_b32 s61, s12, 7
	s_lshl_b32 s61, s61, 8
	s_lshr_b32 s62, s12, 3
	s_add_i32 s61, s61, s62
	v_lshlrev_b32_e32 v110, 5, v102
	s_mov_b32 s46, 0

;     ...
;         const int nitems = (K >> 6) * (N >> 5);
;         int ilo = 0, ihi = nitems; if ((fmask >> mi) & 1u) { ilo = (nitems * flo) >> 4; ihi = (nitems * fhi) >> 4; }
;         const int cnt = ihi - ilo;
;         int first = (gw - base) % NGW; if (first < 0) first += NGW;
;         for (int it = first; it < cnt; it += NGW) tr_item(W, K, N, WT, ks, rm, ilo + it, lane);
;         base = (base + cnt) % NGW;
.Lsl_p0_set0:
	v_readlane_b32 s22, v250, 6
	v_readlane_b32 s23, v250, 7
	v_readlane_b32 s24, v250, 36
	v_readlane_b32 s25, v250, 37
	v_readlane_b32 s44, v250, 4
	v_readlane_b32 s45, v250, 5
	v_mul_u32_u24_e32 v104, 0x3c000, v102
	v_lshl_add_u32 v104, v103, 4, v104
	v_mul_u32_u24_e32 v105, 0x4000, v103
	v_lshl_add_u32 v105, v102, 4, v105
	s_add_u32 s24, s24, 0x1c0000
	s_addc_u32 s25, s25, 0
	s_mov_b32 s48, 0x7800
	s_mov_b32 s49, 0x1e0000
	s_movk_i32 s50, 8739
	s_mov_b32 s51, 21
	s_movk_i32 s52, 240
	s_movk_i32 s53, 0x1000
	s_mov_b32 s54, 3
	s_mov_b32 s55, 1
	s_movk_i32 s56, 0
	s_movk_i32 s47, 7680
	s_sub_i32 s4, s61, 0
	s_and_b32 s4, s4, 2047
	s_branch .Lsl_p0_loop
.Lsl_p0_set1:
	v_readlane_b32 s22, v250, 22
	v_readlane_b32 s23, v250, 23
	v_readlane_b32 s24, v250, 36
	v_readlane_b32 s25, v250, 37
	v_mul_u32_u24_e32 v104, 0x10000, v102
	v_lshl_add_u32 v104, v103, 4, v104
	v_mul_u32_u24_e32 v105, 0x2000, v103
	v_lshl_add_u32 v105, v102, 4, v105
	s_add_u32 s24, s24, 0x3dc0000
	s_addc_u32 s25, s25, 0
	s_mov_b32 s48, 0x2000
	s_mov_b32 s49, 0x80000
	s_movk_i32 s50, 1
	s_mov_b32 s51, 6
	s_movk_i32 s52, 64
	s_movk_i32 s53, 0x800
	s_mov_b32 s54, 0
	s_mov_b32 s55, 0
	s_movk_i32 s56, 0
	s_movk_i32 s47, 1024
	s_sub_i32 s4, s61, 1536
	s_and_b32 s4, s4, 2047
	s_branch .Lsl_p0_loop
.Lsl_p0_set2:
	v_readlane_b32 s22, v250, 24
	v_readlane_b32 s23, v250, 25
	v_readlane_b32 s24, v250, 36
	v_readlane_b32 s25, v250, 37
	v_mul_u32_u24_e32 v104, 0x10000, v102
	v_lshl_add_u32 v104, v103, 4, v104
	v_mul_u32_u24_e32 v105, 0x2000, v103
	v_lshl_add_u32 v105, v102, 4, v105
	s_add_u32 s24, s24, 0x45c0000
	s_addc_u32 s25, s25, 0
	s_mov_b32 s48, 0x2000
	s_mov_b32 s49, 0x80000
	s_movk_i32 s50, 1
	s_mov_b32 s51, 6
	s_movk_i32 s52, 64
	s_movk_i32 s53, 0x800
	s_mov_b32 s54, 0
	s_mov_b32 s55, 0
	s_movk_i32 s56, 0
	s_movk_i32 s47, 1024
	s_sub_i32 s4, s61, 512
	s_and_b32 s4, s4, 2047
	s_branch .Lsl_p0_loop
.Lsl_p0_set3:
	v_readlane_b32 s22, v250, 26
	v_readlane_b32 s23, v250, 27
	v_readlane_b32 s24, v250, 36
	v_readlane_b32 s25, v250, 37
	v_mul_u32_u24_e32 v104, 0x10000, v102
	v_lshl_add_u32 v104, v103, 4, v104
	v_mul_u32_u24_e32 v105, 0x4000, v103
	v_lshl_add_u32 v105, v102, 4, v105
	s_add_u32 s24, s24, 0x4dc0000
	s_addc_u32 s25, s25, 0
	s_mov_b32 s48, 0x2000
	s_mov_b32 s49, 0x80000
	s_movk_i32 s50, 1
	s_mov_b32 s51, 6
	s_movk_i32 s52, 64
	s_movk_i32 s53, 0x1000
	s_mov_b32 s54, 0
	s_mov_b32 s55, 0
	s_movk_i32 s56, 0
	s_movk_i32 s47, 2048
	s_sub_i32 s4, s61, 1536
	s_and_b32 s4, s4, 2047
	s_branch .Lsl_p0_loop

; __global__ void __launch_bounds__(NTHREADS, 2) mk_fwd(Args args) {
;     ...
;             { int thr = S.nwg - ((S.nwg + G - 1) / G - 1) * G; if (thr >= G) thr = 0;
;                 if (blk >= thr) p0_prologue(args, (blk - thr) * NWAVES + wave, (G - thr) * NWAVES, lane, l == 0 ? 0x0030u : 0x1800u, false, l == 0 ? 0x0010u : 0x0800u, 10, 16); }
.LBB0_208:
	v_readlane_b32 s16, v248, 37
	v_readlane_b32 s17, v248, 38
	s_andn2_b64 vcc, exec, s[16:17]
	s_cbranch_vccnz .LBB0_256
	s_cmpk_lg_u32 s3, 0x100
	s_cbranch_scc1 .Lslot_in_orig
	v_readfirstlane_b32 s2, v204
	v_and_b32_e32 v43, 63, v204
	v_lshrrev_b32_e32 v102, 3, v43
	v_and_b32_e32 v103, 7, v43
	s_lshr_b32 s2, s2, 6
	s_mul_i32 s2, s2, 64
	s_sub_i32 s19, s85, 192
	s_add_i32 s2, s2, s19
	v_lshlrev_b32_e32 v110, 5, v102
	s_mov_b32 s28, 0
	s_cmp_lg_u32 s64, 0
	s_cselect_b32 s28, 16, 0

; __global__ void __launch_bounds__(NTHREADS, 2) mk_fwd(Args args) {
;     ...
;             { int thr = S.nwg - ((S.nwg + G - 1) / G - 1) * G; if (thr >= G) thr = 0;
;                 if (blk >= thr) p0_prologue(args, (blk - thr) * NWAVES + wave, (G - thr) * NWAVES, lane, l == 0 ? 0x07C0u : 0x2000u, false); }
.LBB0_670:
	v_readlane_b32 s6, v248, 44
	v_readlane_b32 s7, v248, 45
	s_andn2_b64 vcc, exec, s[6:7]
	s_cbranch_vccnz .LBB0_716
	s_cmpk_lg_u32 s3, 0x100
	s_cbranch_scc1 .Lslot_gu_orig
	v_readfirstlane_b32 s2, v204
	v_and_b32_e32 v43, 63, v204
	v_lshrrev_b32_e32 v102, 3, v43
	v_and_b32_e32 v103, 7, v43
	s_lshr_b32 s2, s2, 6
	s_mul_i32 s2, s2, 128
	s_sub_i32 s19, s85, 128
	s_add_i32 s2, s2, s19
	v_lshlrev_b32_e32 v110, 5, v102
	s_mov_b32 s28, 0
	s_cmp_lg_u32 s64, 0
	s_cselect_b32 s28, 16, 0
